# FFN1 GEMM loop: LDS-DMA loads use SGPR base + 32-bit VGPR offset (removes 16 64-bit VALU adds per iteration from the loader wave)
# speedup vs baseline: 1.0177x; 1.0013x over previous
; #define PG8_STAGE(bufoff, gbase, voff) do { _Pragma("unroll") for (int _i = 0; _i < 2; ++_i) \
;         __builtin_amdgcn_global_load_lds((const unsigned*)((const char*)(gbase) + (voff)[_i]), (PG8_LAS unsigned*)(lds + (bufoff) + ldsw + _i * 8192), 16, 0, 0); } while (0)
; #define PG8_LDA(dst, b, h) do { _Pragma("unroll") for (int m = 0; m < 4; ++m) _Pragma("unroll") for (int k = 0; k < 2; ++k) dst[m][k] = *(const PG8_LAS bf16x8*)(lds + PG8_SA(b, h) + aoff + m * 2048 + k * 1024); } while (0)
; #define PG8_LDB(dst, b, h) do { _Pragma("unroll") for (int n = 0; n < 2; ++n) _Pragma("unroll") for (int k = 0; k < 2; ++k) dst[n][k] = *(const PG8_LAS bf16x8*)(lds + PG8_SB(b, h) + boff + n * 2048 + k * 1024); } while (0)
; #define PG8_MMA(ai, bj, At, Bt) do { __builtin_amdgcn_s_setprio(1); _Pragma("unroll") for (int m = 0; m < 4; ++m) _Pragma("unroll") for (int n = 0; n < 2; ++n) _Pragma("unroll") for (int k = 0; k < 2; ++k) \
;         acc[ai][bj][m][n] = __builtin_amdgcn_mfma_f32_16x16x32_bf16(Bt[n][k], At[m][k], acc[ai][bj][m][n], 0, 0, 0); __builtin_amdgcn_s_setprio(0); } while (0)
; #define PG8_WAIT_V(n) asm volatile("s_waitcnt vmcnt(" #n ")" ::: "memory")
; #define PG8_WAIT_L(n) asm volatile("s_waitcnt lgkmcnt(" #n ")" ::: "memory")
; #define PG8_BAR __builtin_amdgcn_s_barrier()
; #define PG8_SCHED __builtin_amdgcn_sched_barrier(0)
; template <class Epi, class Sched, bool ALIGN_EPI = false, bool SP2 = false>
; __device__ __forceinline__ void gemm_phase(PG8_LAS unsigned char* lds, const Gemm g, const Sched& S, const Epi& E) {
;     ...
;             PG8_LDB(B0, 0, 0); PG8_LDB(B1, 0, 1); PG8_SCHED; PG8_LDA(At, 0, 0); PG8_STAGE(PG8_SA(1, 1), a1 + hstep, voffA);
;             PG8_WAIT_V(8); PG8_WAIT_L(0); PG8_BAR; PG8_MMA(0, 0, At, B0); PG8_MMA(0, 1, At, B1); PG8_BAR; PG8_SCHED;
;             PG8_LDA(At, 0, 1); PG8_STAGE(PG8_SB(0, 0), b2, voffB); PG8_STAGE(PG8_SB(0, 1), b2 + hstep, voffB); PG8_STAGE(PG8_SA(0, 0), a2, voffA);
;             PG8_WAIT_V(8); PG8_WAIT_L(0); PG8_BAR; PG8_MMA(1, 0, At, B0); PG8_MMA(1, 1, At, B1); PG8_BAR; PG8_SCHED;
.LBB0_402:
	s_add_u32 s36, s18, 0x100
	s_addc_u32 s37, s19, 0
	s_add_i32 s47, 0, 0x10000
	s_cmp_eq_u32 s43, 28
	s_cselect_b32 s39, s9, s37
	s_cselect_b32 s38, s8, s36
	s_cselect_b32 s5, s17, s41
	s_cselect_b32 s4, s16, s31
	s_add_i32 s92, 0, 0x14000
	v_add_u32_e32 v156, s47, v1
	v_add_u32_e32 v172, s92, v1
	ds_read_b128 v[144:147], v156
	ds_read_b128 v[148:151], v156 offset:1024
	ds_read_b128 v[152:155], v156 offset:2048
	ds_read_b128 v[156:159], v156 offset:3072
	ds_read_b128 v[160:163], v172
	ds_read_b128 v[164:167], v172 offset:1024
	ds_read_b128 v[168:171], v172 offset:2048
	ds_read_b128 v[172:175], v172 offset:3072
	s_add_i32 m0, s54, 0xc000
	ds_read_b128 v[176:179], v17
	ds_read_b128 v[180:183], v17 offset:1024
	ds_read_b128 v[184:187], v17 offset:2048
	ds_read_b128 v[188:191], v17 offset:3072
	ds_read_b128 v[192:195], v17 offset:4096
	ds_read_b128 v[196:199], v17 offset:5120
	ds_read_b128 v[200:203], v17 offset:6144
	ds_read_b128 v[204:207], v17 offset:7168
	global_load_lds_dwordx4 v142, s[18:19]
	s_add_i32 m0, s54, 0xe000
	s_nop 0
	global_load_lds_dwordx4 v140, s[18:19]
	s_waitcnt vmcnt(8)
	s_waitcnt lgkmcnt(0)
	s_barrier
	s_setprio 1
	s_waitcnt lgkmcnt(0)
	v_mfma_f32_16x16x32_bf16 v[130:133], v[144:147], v[176:179], v[130:133]
	v_mfma_f32_16x16x32_bf16 v[122:125], v[152:155], v[176:179], v[122:125]
	v_mfma_f32_16x16x32_bf16 v[114:117], v[144:147], v[184:187], v[114:117]
	v_mfma_f32_16x16x32_bf16 v[106:109], v[152:155], v[184:187], v[106:109]
	v_mfma_f32_16x16x32_bf16 v[98:101], v[144:147], v[192:195], v[98:101]
	v_mfma_f32_16x16x32_bf16 v[90:93], v[152:155], v[192:195], v[90:93]
	v_mfma_f32_16x16x32_bf16 v[82:85], v[144:147], v[200:203], v[82:85]
	v_mfma_f32_16x16x32_bf16 v[74:77], v[152:155], v[200:203], v[74:77]
	v_mfma_f32_16x16x32_bf16 v[130:133], v[148:151], v[180:183], v[130:133]
	v_mfma_f32_16x16x32_bf16 v[122:125], v[156:159], v[180:183], v[122:125]
	v_mfma_f32_16x16x32_bf16 v[114:117], v[148:151], v[188:191], v[114:117]
	v_mfma_f32_16x16x32_bf16 v[106:109], v[156:159], v[188:191], v[106:109]
	v_mfma_f32_16x16x32_bf16 v[98:101], v[148:151], v[196:199], v[98:101]
	v_mfma_f32_16x16x32_bf16 v[90:93], v[156:159], v[196:199], v[90:93]
	v_mfma_f32_16x16x32_bf16 v[82:85], v[148:151], v[204:207], v[82:85]
	v_mfma_f32_16x16x32_bf16 v[74:77], v[156:159], v[204:207], v[74:77]
	s_setprio 0
	s_setprio 1
	v_mfma_f32_16x16x32_bf16 v[126:129], v[160:163], v[176:179], v[126:129]
	v_mfma_f32_16x16x32_bf16 v[118:121], v[168:171], v[176:179], v[118:121]
	v_mfma_f32_16x16x32_bf16 v[110:113], v[160:163], v[184:187], v[110:113]
	v_mfma_f32_16x16x32_bf16 v[102:105], v[168:171], v[184:187], v[102:105]
	v_mfma_f32_16x16x32_bf16 v[94:97], v[160:163], v[192:195], v[94:97]
	v_mfma_f32_16x16x32_bf16 v[86:89], v[168:171], v[192:195], v[86:89]
	v_mfma_f32_16x16x32_bf16 v[78:81], v[160:163], v[200:203], v[78:81]
	v_mfma_f32_16x16x32_bf16 v[70:73], v[168:171], v[200:203], v[70:73]
	v_mfma_f32_16x16x32_bf16 v[126:129], v[164:167], v[180:183], v[126:129]
	v_mfma_f32_16x16x32_bf16 v[118:121], v[172:175], v[180:183], v[118:121]
	v_mfma_f32_16x16x32_bf16 v[110:113], v[164:167], v[188:191], v[110:113]
	v_mfma_f32_16x16x32_bf16 v[102:105], v[172:175], v[188:191], v[102:105]
	v_mfma_f32_16x16x32_bf16 v[94:97], v[164:167], v[196:199], v[94:97]
	v_mfma_f32_16x16x32_bf16 v[86:89], v[172:175], v[196:199], v[86:89]
	v_mfma_f32_16x16x32_bf16 v[78:81], v[164:167], v[204:207], v[78:81]
	v_mfma_f32_16x16x32_bf16 v[70:73], v[172:175], v[204:207], v[70:73]
	s_setprio 0
	s_barrier
	s_add_i32 s18, s47, s46
	s_mov_b32 m0, s18
	ds_read_b128 v[176:179], v17 offset:16384
	ds_read_b128 v[180:183], v17 offset:17408
	ds_read_b128 v[184:187], v17 offset:18432
	ds_read_b128 v[188:191], v17 offset:19456
	ds_read_b128 v[192:195], v17 offset:20480
	ds_read_b128 v[196:199], v17 offset:21504
	ds_read_b128 v[200:203], v17 offset:22528
	ds_read_b128 v[204:207], v17 offset:23552
	global_load_lds_dwordx4 v136, s[4:5]
	s_add_i32 m0, s18, 0x2000
	s_add_u32 s18, s4, 0x84000
	s_addc_u32 s19, s5, 0
	s_add_i32 s47, s92, s46
	global_load_lds_dwordx4 v14, s[4:5]
	s_mov_b32 m0, s47
	s_nop 0
	global_load_lds_dwordx4 v136, s[18:19]
	s_add_i32 m0, s47, 0x2000
	s_nop 0
	global_load_lds_dwordx4 v14, s[18:19]
	s_mov_b32 m0, s54
	s_nop 0
	global_load_lds_dwordx4 v138, s[38:39]
	s_mov_b32 m0, s64
	s_nop 0
	global_load_lds_dwordx4 v134, s[38:39]
	s_waitcnt vmcnt(8)
	s_waitcnt lgkmcnt(0)
	s_barrier
	s_setprio 1
	s_waitcnt lgkmcnt(0)
	v_mfma_f32_16x16x32_bf16 v[66:69], v[144:147], v[176:179], v[66:69]
	v_mfma_f32_16x16x32_bf16 v[58:61], v[152:155], v[176:179], v[58:61]
	v_mfma_f32_16x16x32_bf16 v[50:53], v[144:147], v[184:187], v[50:53]
	v_mfma_f32_16x16x32_bf16 v[42:45], v[152:155], v[184:187], v[42:45]
	v_mfma_f32_16x16x32_bf16 v[34:37], v[144:147], v[192:195], v[34:37]
	v_mfma_f32_16x16x32_bf16 v[26:29], v[152:155], v[192:195], v[26:29]
	v_mfma_f32_16x16x32_bf16 v[18:21], v[144:147], v[200:203], v[18:21]
	v_mfma_f32_16x16x32_bf16 v[6:9], v[152:155], v[200:203], v[6:9]
	v_mfma_f32_16x16x32_bf16 v[66:69], v[148:151], v[180:183], v[66:69]
	v_mfma_f32_16x16x32_bf16 v[58:61], v[156:159], v[180:183], v[58:61]
	v_mfma_f32_16x16x32_bf16 v[50:53], v[148:151], v[188:191], v[50:53]
	v_mfma_f32_16x16x32_bf16 v[42:45], v[156:159], v[188:191], v[42:45]
	v_mfma_f32_16x16x32_bf16 v[34:37], v[148:151], v[196:199], v[34:37]
	v_mfma_f32_16x16x32_bf16 v[26:29], v[156:159], v[196:199], v[26:29]
	v_mfma_f32_16x16x32_bf16 v[18:21], v[148:151], v[204:207], v[18:21]
	v_mfma_f32_16x16x32_bf16 v[6:9], v[156:159], v[204:207], v[6:9]
	s_setprio 0
	s_setprio 1
	v_mfma_f32_16x16x32_bf16 v[62:65], v[160:163], v[176:179], v[62:65]
	v_mfma_f32_16x16x32_bf16 v[54:57], v[168:171], v[176:179], v[54:57]
	v_mfma_f32_16x16x32_bf16 v[46:49], v[160:163], v[184:187], v[46:49]
	v_mfma_f32_16x16x32_bf16 v[38:41], v[168:171], v[184:187], v[38:41]
	v_mfma_f32_16x16x32_bf16 v[30:33], v[160:163], v[192:195], v[30:33]
	v_mfma_f32_16x16x32_bf16 v[22:25], v[168:171], v[192:195], v[22:25]
	v_mfma_f32_16x16x32_bf16 v[10:13], v[160:163], v[200:203], v[10:13]
	v_mfma_f32_16x16x32_bf16 v[2:5], v[168:171], v[200:203], v[2:5]
	v_mfma_f32_16x16x32_bf16 v[62:65], v[164:167], v[180:183], v[62:65]
	v_mfma_f32_16x16x32_bf16 v[54:57], v[172:175], v[180:183], v[54:57]
	v_mfma_f32_16x16x32_bf16 v[46:49], v[164:167], v[188:191], v[46:49]
	v_mfma_f32_16x16x32_bf16 v[38:41], v[172:175], v[188:191], v[38:41]
	v_mfma_f32_16x16x32_bf16 v[30:33], v[164:167], v[196:199], v[30:33]
	v_mfma_f32_16x16x32_bf16 v[22:25], v[172:175], v[196:199], v[22:25]
	v_mfma_f32_16x16x32_bf16 v[10:13], v[164:167], v[204:207], v[10:13]
	v_mfma_f32_16x16x32_bf16 v[2:5], v[172:175], v[204:207], v[2:5]
	s_setprio 0
	s_barrier
; #define PG8_STAGE(bufoff, gbase, voff) do { _Pragma("unroll") for (int _i = 0; _i < 2; ++_i) \
;         __builtin_amdgcn_global_load_lds((const unsigned*)((const char*)(gbase) + (voff)[_i]), (PG8_LAS unsigned*)(lds + (bufoff) + ldsw + _i * 8192), 16, 0, 0); } while (0)
; #define PG8_LDA(dst, b, h) do { _Pragma("unroll") for (int m = 0; m < 4; ++m) _Pragma("unroll") for (int k = 0; k < 2; ++k) dst[m][k] = *(const PG8_LAS bf16x8*)(lds + PG8_SA(b, h) + aoff + m * 2048 + k * 1024); } while (0)
; #define PG8_LDB(dst, b, h) do { _Pragma("unroll") for (int n = 0; n < 2; ++n) _Pragma("unroll") for (int k = 0; k < 2; ++k) dst[n][k] = *(const PG8_LAS bf16x8*)(lds + PG8_SB(b, h) + boff + n * 2048 + k * 1024); } while (0)
; #define PG8_MMA(ai, bj, At, Bt) do { __builtin_amdgcn_s_setprio(1); _Pragma("unroll") for (int m = 0; m < 4; ++m) _Pragma("unroll") for (int n = 0; n < 2; ++n) _Pragma("unroll") for (int k = 0; k < 2; ++k) \
;         acc[ai][bj][m][n] = __builtin_amdgcn_mfma_f32_16x16x32_bf16(Bt[n][k], At[m][k], acc[ai][bj][m][n], 0, 0, 0); __builtin_amdgcn_s_setprio(0); } while (0)
; #define PG8_WAIT_V(n) asm volatile("s_waitcnt vmcnt(" #n ")" ::: "memory")
; #define PG8_WAIT_L(n) asm volatile("s_waitcnt lgkmcnt(" #n ")" ::: "memory")
; #define PG8_BAR __builtin_amdgcn_s_barrier()
; #define PG8_SCHED __builtin_amdgcn_sched_barrier(0)
; template <class Epi, class Sched, bool ALIGN_EPI = false, bool SP2 = false>
; __device__ __forceinline__ void gemm_phase(PG8_LAS unsigned char* lds, const Gemm g, const Sched& S, const Epi& E) {
;     ...
;             PG8_LDB(B0, 1, 0); PG8_LDB(B1, 1, 1); PG8_SCHED; PG8_LDA(At, 1, 0); PG8_STAGE(PG8_SA(0, 1), a2 + hstep, voffA);
;             PG8_WAIT_V(8); PG8_WAIT_L(0); PG8_BAR; PG8_MMA(0, 0, At, B0); PG8_MMA(0, 1, At, B1); PG8_BAR; PG8_SCHED;
;             PG8_LDA(At, 1, 1); PG8_STAGE(PG8_SB(1, 0), b3, voffB); PG8_STAGE(PG8_SB(1, 1), b3 + hstep, voffB); PG8_STAGE(PG8_SA(1, 0), a3, voffA);
;             PG8_WAIT_V(8); PG8_WAIT_L(0); PG8_BAR; PG8_MMA(1, 0, At, B0); PG8_MMA(1, 1, At, B1); PG8_BAR; PG8_SCHED;
	s_add_i32 s47, 0, 0x18000
	s_add_i32 s92, 0, 0x1c000
	v_add_u32_e32 v156, s47, v1
	v_add_u32_e32 v172, s92, v1
	ds_read_b128 v[144:147], v156
	ds_read_b128 v[148:151], v156 offset:1024
	ds_read_b128 v[152:155], v156 offset:2048
	ds_read_b128 v[156:159], v156 offset:3072
	ds_read_b128 v[160:163], v172
	ds_read_b128 v[164:167], v172 offset:1024
	ds_read_b128 v[168:171], v172 offset:2048
	ds_read_b128 v[172:175], v172 offset:3072
	s_add_u32 s18, s38, 0x84000
	s_addc_u32 s19, s39, 0
	s_mov_b32 m0, s65
	ds_read_b128 v[176:179], v17 offset:32768
	ds_read_b128 v[180:183], v17 offset:33792
	ds_read_b128 v[184:187], v17 offset:34816
	ds_read_b128 v[188:191], v17 offset:35840
	ds_read_b128 v[192:195], v17 offset:36864
	ds_read_b128 v[196:199], v17 offset:37888
	ds_read_b128 v[200:203], v17 offset:38912
	ds_read_b128 v[204:207], v17 offset:39936
	global_load_lds_dwordx4 v138, s[18:19]
	s_mov_b32 m0, s68
	s_nop 0
	global_load_lds_dwordx4 v134, s[18:19]
	s_waitcnt vmcnt(8)
	s_waitcnt lgkmcnt(0)
	s_barrier
	s_setprio 1
	s_waitcnt lgkmcnt(0)
	v_mfma_f32_16x16x32_bf16 v[130:133], v[144:147], v[176:179], v[130:133]
	v_mfma_f32_16x16x32_bf16 v[122:125], v[152:155], v[176:179], v[122:125]
	v_mfma_f32_16x16x32_bf16 v[114:117], v[144:147], v[184:187], v[114:117]
	v_mfma_f32_16x16x32_bf16 v[106:109], v[152:155], v[184:187], v[106:109]
	v_mfma_f32_16x16x32_bf16 v[98:101], v[144:147], v[192:195], v[98:101]
	v_mfma_f32_16x16x32_bf16 v[90:93], v[152:155], v[192:195], v[90:93]
	v_mfma_f32_16x16x32_bf16 v[82:85], v[144:147], v[200:203], v[82:85]
	v_mfma_f32_16x16x32_bf16 v[74:77], v[152:155], v[200:203], v[74:77]
	v_mfma_f32_16x16x32_bf16 v[130:133], v[148:151], v[180:183], v[130:133]
	v_mfma_f32_16x16x32_bf16 v[122:125], v[156:159], v[180:183], v[122:125]
	v_mfma_f32_16x16x32_bf16 v[114:117], v[148:151], v[188:191], v[114:117]
	v_mfma_f32_16x16x32_bf16 v[106:109], v[156:159], v[188:191], v[106:109]
	v_mfma_f32_16x16x32_bf16 v[98:101], v[148:151], v[196:199], v[98:101]
	v_mfma_f32_16x16x32_bf16 v[90:93], v[156:159], v[196:199], v[90:93]
	v_mfma_f32_16x16x32_bf16 v[82:85], v[148:151], v[204:207], v[82:85]
	v_mfma_f32_16x16x32_bf16 v[74:77], v[156:159], v[204:207], v[74:77]
	s_setprio 0
	s_setprio 1
	v_mfma_f32_16x16x32_bf16 v[126:129], v[160:163], v[176:179], v[126:129]
	v_mfma_f32_16x16x32_bf16 v[118:121], v[168:171], v[176:179], v[118:121]
	v_mfma_f32_16x16x32_bf16 v[110:113], v[160:163], v[184:187], v[110:113]
	v_mfma_f32_16x16x32_bf16 v[102:105], v[168:171], v[184:187], v[102:105]
	v_mfma_f32_16x16x32_bf16 v[94:97], v[160:163], v[192:195], v[94:97]
	v_mfma_f32_16x16x32_bf16 v[86:89], v[168:171], v[192:195], v[86:89]
	v_mfma_f32_16x16x32_bf16 v[78:81], v[160:163], v[200:203], v[78:81]
	v_mfma_f32_16x16x32_bf16 v[70:73], v[168:171], v[200:203], v[70:73]
	v_mfma_f32_16x16x32_bf16 v[126:129], v[164:167], v[180:183], v[126:129]
	v_mfma_f32_16x16x32_bf16 v[118:121], v[172:175], v[180:183], v[118:121]
	v_mfma_f32_16x16x32_bf16 v[110:113], v[164:167], v[188:191], v[110:113]
	v_mfma_f32_16x16x32_bf16 v[102:105], v[172:175], v[188:191], v[102:105]
	v_mfma_f32_16x16x32_bf16 v[94:97], v[164:167], v[196:199], v[94:97]
	v_mfma_f32_16x16x32_bf16 v[86:89], v[172:175], v[196:199], v[86:89]
	v_mfma_f32_16x16x32_bf16 v[78:81], v[164:167], v[204:207], v[78:81]
	v_mfma_f32_16x16x32_bf16 v[70:73], v[172:175], v[204:207], v[70:73]
	s_setprio 0
	s_barrier
	s_add_i32 s18, s47, s46
	s_add_u32 s4, s4, 0x80
	s_addc_u32 s5, s5, 0
	s_mov_b32 m0, s18
	ds_read_b128 v[176:179], v17 offset:49152
	ds_read_b128 v[180:183], v17 offset:50176
	ds_read_b128 v[184:187], v17 offset:51200
	ds_read_b128 v[188:191], v17 offset:52224
	ds_read_b128 v[192:195], v17 offset:53248
	ds_read_b128 v[196:199], v17 offset:54272
	ds_read_b128 v[200:203], v17 offset:55296
	ds_read_b128 v[204:207], v17 offset:56320
	global_load_lds_dwordx4 v136, s[4:5]
	s_add_i32 m0, s18, 0x2000
	s_add_i32 s18, s92, s46
	global_load_lds_dwordx4 v14, s[4:5]
	s_add_u32 s4, s4, 0x84000
	s_addc_u32 s5, s5, 0
	s_mov_b32 m0, s18
	s_nop 0
	global_load_lds_dwordx4 v136, s[4:5]
	s_add_i32 m0, s18, 0x2000
	s_nop 0
	global_load_lds_dwordx4 v14, s[4:5]
	s_add_i32 m0, s54, 0x7f80
	s_nop 0
	global_load_lds_dwordx4 v138, s[38:39] offset:128
	s_add_i32 m0, s54, 0x9f80
	s_nop 0
	global_load_lds_dwordx4 v134, s[38:39] offset:128
	s_waitcnt vmcnt(8)
	s_waitcnt lgkmcnt(0)
	s_barrier
	s_setprio 1
	s_waitcnt lgkmcnt(0)
	v_mfma_f32_16x16x32_bf16 v[66:69], v[144:147], v[176:179], v[66:69]
	v_mfma_f32_16x16x32_bf16 v[58:61], v[152:155], v[176:179], v[58:61]
	v_mfma_f32_16x16x32_bf16 v[50:53], v[144:147], v[184:187], v[50:53]
	v_mfma_f32_16x16x32_bf16 v[42:45], v[152:155], v[184:187], v[42:45]
	v_mfma_f32_16x16x32_bf16 v[34:37], v[144:147], v[192:195], v[34:37]
	v_mfma_f32_16x16x32_bf16 v[26:29], v[152:155], v[192:195], v[26:29]
	v_mfma_f32_16x16x32_bf16 v[18:21], v[144:147], v[200:203], v[18:21]
	v_mfma_f32_16x16x32_bf16 v[6:9], v[152:155], v[200:203], v[6:9]
	v_mfma_f32_16x16x32_bf16 v[66:69], v[148:151], v[180:183], v[66:69]
	v_mfma_f32_16x16x32_bf16 v[58:61], v[156:159], v[180:183], v[58:61]
	v_mfma_f32_16x16x32_bf16 v[50:53], v[148:151], v[188:191], v[50:53]
	v_mfma_f32_16x16x32_bf16 v[42:45], v[156:159], v[188:191], v[42:45]
	v_mfma_f32_16x16x32_bf16 v[34:37], v[148:151], v[196:199], v[34:37]
	v_mfma_f32_16x16x32_bf16 v[26:29], v[156:159], v[196:199], v[26:29]
	v_mfma_f32_16x16x32_bf16 v[18:21], v[148:151], v[204:207], v[18:21]
	v_mfma_f32_16x16x32_bf16 v[6:9], v[156:159], v[204:207], v[6:9]
	s_setprio 0
	s_setprio 1
	v_mfma_f32_16x16x32_bf16 v[62:65], v[160:163], v[176:179], v[62:65]
	v_mfma_f32_16x16x32_bf16 v[54:57], v[168:171], v[176:179], v[54:57]
	v_mfma_f32_16x16x32_bf16 v[46:49], v[160:163], v[184:187], v[46:49]
	v_mfma_f32_16x16x32_bf16 v[38:41], v[168:171], v[184:187], v[38:41]
	v_mfma_f32_16x16x32_bf16 v[30:33], v[160:163], v[192:195], v[30:33]
	v_mfma_f32_16x16x32_bf16 v[22:25], v[168:171], v[192:195], v[22:25]
	v_mfma_f32_16x16x32_bf16 v[10:13], v[160:163], v[200:203], v[10:13]
	v_mfma_f32_16x16x32_bf16 v[2:5], v[168:171], v[200:203], v[2:5]
	v_mfma_f32_16x16x32_bf16 v[62:65], v[164:167], v[180:183], v[62:65]
	v_mfma_f32_16x16x32_bf16 v[54:57], v[172:175], v[180:183], v[54:57]
	v_mfma_f32_16x16x32_bf16 v[46:49], v[164:167], v[188:191], v[46:49]
	v_mfma_f32_16x16x32_bf16 v[38:41], v[172:175], v[188:191], v[38:41]
	v_mfma_f32_16x16x32_bf16 v[30:33], v[164:167], v[196:199], v[30:33]
	v_mfma_f32_16x16x32_bf16 v[22:25], v[172:175], v[196:199], v[22:25]
	v_mfma_f32_16x16x32_bf16 v[10:13], v[164:167], v[204:207], v[10:13]
	v_mfma_f32_16x16x32_bf16 v[2:5], v[172:175], v[204:207], v[2:5]
	s_setprio 0
	s_barrier
	s_add_i32 s43, s43, 2
	s_add_u32 s31, s31, 0x100
	s_addc_u32 s41, s41, 0
	s_cmp_gt_u32 s43, 29
	s_mov_b64 s[18:19], s[36:37]
	s_cbranch_scc0 .LBB0_402
	s_and_b64 vcc, exec, s[14:15]
	s_cbranch_vccz .LBB0_405
	s_barrier
